# P8 GEMM K-loop: each LDS-DMA stage waited 5 phases after issue (vmcnt(10) before six mid-phase barriers) instead of two bulk vmcnt(6) waits
# baseline (speedup 1.0000x reference)
; #define PG8_STAGE(bufoff, gbase, voff) do { _Pragma("unroll") for (int _i = 0; _i < 2; ++_i) \
;         __builtin_amdgcn_global_load_lds((const unsigned*)((const char*)(gbase) + (voff)[_i]), (PG8_LAS unsigned*)(lds + (bufoff) + ldsw + _i * 8192), 16, 0, 0); } while (0)
; #define PG8_LDA(dst, b, h) do { _Pragma("unroll") for (int m = 0; m < 4; ++m) _Pragma("unroll") for (int k = 0; k < 2; ++k) dst[m][k] = *(const PG8_LAS bf16x8*)(lds + PG8_SA(b, h) + aoff + m * 2048 + k * 1024); } while (0)
; #define PG8_LDB(dst, b, h) do { _Pragma("unroll") for (int n = 0; n < 2; ++n) _Pragma("unroll") for (int k = 0; k < 2; ++k) dst[n][k] = *(const PG8_LAS bf16x8*)(lds + PG8_SB(b, h) + boff + n * 2048 + k * 1024); } while (0)
; #define PG8_MMA(ai, bj, At, Bt) do { __builtin_amdgcn_s_setprio(1); _Pragma("unroll") for (int m = 0; m < 4; ++m) _Pragma("unroll") for (int n = 0; n < 2; ++n) _Pragma("unroll") for (int k = 0; k < 2; ++k) \
;         acc[ai][bj][m][n] = __builtin_amdgcn_mfma_f32_16x16x32_bf16(Bt[n][k], At[m][k], acc[ai][bj][m][n], 0, 0, 0); __builtin_amdgcn_s_setprio(0); } while (0)
; #define PG8_WAIT_L(n) asm volatile("s_waitcnt lgkmcnt(" #n ")" ::: "memory")
; #define PG8_BAR __builtin_amdgcn_s_barrier()
; #define PG8_SCHED __builtin_amdgcn_sched_barrier(0)
; template <class Epi>
; __device__ __forceinline__ void gemm_phase(PG8_LAS unsigned char* lds, const Gemm g, const StaticOrder& S, const Epi& E) {
;     ...
;         for (int t = 0; t < nt; t += 2) {
;             const bool last = (t == nt - 2);
;             const char* a1 = cA + (size_t)(t + 1) * kstep;
;             const char* a2 = last ? nA : cA + (size_t)(t + 2) * kstep; const char* b2 = last ? nB : cB + (size_t)(t + 2) * kstep;
;             const char* a3 = a2 + kstep; const char* b3 = b2 + kstep;
;             PG8_LDB(B0, 0, 0); PG8_SCHED; PG8_LDA(At, 0, 0); PG8_STAGE(PG8_SA(1, 1), a1 + hstep, voffA);
;             PG8_WAIT_L(8); PG8_BAR; PG8_WAIT_L(0); PG8_MMA(0, 0, At, B0); PG8_BAR; PG8_SCHED;
;             PG8_LDB(B1, 0, 1); PG8_STAGE(PG8_SB(0, 0), b2, voffB);
;             PG8_BAR; PG8_WAIT_L(0); PG8_MMA(0, 1, At, B1); PG8_BAR;
;             PG8_LDA(At, 0, 1); PG8_STAGE(PG8_SA(0, 0), a2, voffA);
;             PG8_BAR; PG8_WAIT_L(0); PG8_MMA(1, 0, At, B0); PG8_BAR; PG8_SCHED;
.LBB0_722:
	ds_read_b128 v[150:153], v159
	ds_read_b128 v[154:157], v159 offset:1024
	ds_read_b128 v[162:165], v159 offset:2048
	ds_read_b128 v[166:169], v159 offset:3072
	s_add_u32 s22, s20, 0xfff80080
	s_addc_u32 s23, s21, -1
	s_cmp_eq_u32 s50, 28
	s_cselect_b32 s25, s3, s23
	s_cselect_b32 s24, s5, s22
	s_cselect_b32 s23, s13, s49
	s_cselect_b32 s22, s15, s48
	v_lshl_add_u64 v[202:203], s[20:21], 0, v[142:143]
	s_add_i32 m0, s30, 0xc000
	ds_read_b128 v[170:173], v160
	ds_read_b128 v[174:177], v160 offset:1024
	ds_read_b128 v[178:181], v160 offset:2048
	ds_read_b128 v[182:185], v160 offset:3072
	ds_read_b128 v[186:189], v160 offset:4096
	ds_read_b128 v[190:193], v160 offset:5120
	ds_read_b128 v[194:197], v160 offset:6144
	ds_read_b128 v[198:201], v160 offset:7168
	global_load_lds_dwordx4 v[202:203], off
	v_lshl_add_u64 v[202:203], s[20:21], 0, v[144:145]
	s_add_i32 m0, s30, 0xe000
	s_nop 0
	global_load_lds_dwordx4 v[202:203], off
	s_waitcnt lgkmcnt(8)
	s_waitcnt vmcnt(10)
	s_barrier
	s_waitcnt lgkmcnt(0)
	s_setprio 1
	s_waitcnt lgkmcnt(0)
	v_mfma_f32_16x16x32_bf16 v[126:129], v[150:153], v[170:173], v[126:129]
	v_mfma_f32_16x16x32_bf16 v[122:125], v[162:165], v[170:173], v[122:125]
	v_mfma_f32_16x16x32_bf16 v[110:113], v[150:153], v[178:181], v[110:113]
	v_mfma_f32_16x16x32_bf16 v[106:109], v[162:165], v[178:181], v[106:109]
	v_mfma_f32_16x16x32_bf16 v[94:97], v[150:153], v[186:189], v[94:97]
	v_mfma_f32_16x16x32_bf16 v[90:93], v[162:165], v[186:189], v[90:93]
	v_mfma_f32_16x16x32_bf16 v[78:81], v[150:153], v[194:197], v[78:81]
	v_mfma_f32_16x16x32_bf16 v[74:77], v[162:165], v[194:197], v[74:77]
	v_mfma_f32_16x16x32_bf16 v[126:129], v[154:157], v[174:177], v[126:129]
	v_mfma_f32_16x16x32_bf16 v[122:125], v[166:169], v[174:177], v[122:125]
	v_mfma_f32_16x16x32_bf16 v[110:113], v[154:157], v[182:185], v[110:113]
	v_mfma_f32_16x16x32_bf16 v[106:109], v[166:169], v[182:185], v[106:109]
	v_mfma_f32_16x16x32_bf16 v[94:97], v[154:157], v[190:193], v[94:97]
	v_mfma_f32_16x16x32_bf16 v[90:93], v[166:169], v[190:193], v[90:93]
	v_mfma_f32_16x16x32_bf16 v[78:81], v[154:157], v[198:201], v[78:81]
	v_mfma_f32_16x16x32_bf16 v[74:77], v[166:169], v[198:201], v[74:77]
	s_setprio 0
	s_barrier
	s_add_i32 s51, s43, s29
	v_lshl_add_u64 v[218:219], s[22:23], 0, v[134:135]
	s_mov_b32 m0, s51
	ds_read_b128 v[202:205], v161
	ds_read_b128 v[206:209], v161 offset:1024
	ds_read_b128 v[210:213], v161 offset:2048
	ds_read_b128 v[214:217], v161 offset:3072
	global_load_lds_dwordx4 v[218:219], off
	v_lshl_add_u64 v[220:221], s[22:23], 0, v[138:139]
	s_add_i32 m0, s51, 0x2000
	s_nop 0
	global_load_lds_dwordx4 v[220:221], off
	s_waitcnt vmcnt(10)
	s_barrier
	s_waitcnt lgkmcnt(0)
	s_setprio 1
	s_waitcnt lgkmcnt(0)
	v_mfma_f32_16x16x32_bf16 v[118:121], v[202:205], v[170:173], v[118:121]
	v_mfma_f32_16x16x32_bf16 v[114:117], v[210:213], v[170:173], v[114:117]
	v_mfma_f32_16x16x32_bf16 v[102:105], v[202:205], v[178:181], v[102:105]
	v_mfma_f32_16x16x32_bf16 v[98:101], v[210:213], v[178:181], v[98:101]
	v_mfma_f32_16x16x32_bf16 v[86:89], v[202:205], v[186:189], v[86:89]
	v_mfma_f32_16x16x32_bf16 v[82:85], v[210:213], v[186:189], v[82:85]
	v_mfma_f32_16x16x32_bf16 v[70:73], v[202:205], v[194:197], v[70:73]
	v_mfma_f32_16x16x32_bf16 v[66:69], v[210:213], v[194:197], v[66:69]
	v_mfma_f32_16x16x32_bf16 v[118:121], v[206:209], v[174:177], v[118:121]
	v_mfma_f32_16x16x32_bf16 v[114:117], v[214:217], v[174:177], v[114:117]
	v_mfma_f32_16x16x32_bf16 v[102:105], v[206:209], v[182:185], v[102:105]
	v_mfma_f32_16x16x32_bf16 v[98:101], v[214:217], v[182:185], v[98:101]
	v_mfma_f32_16x16x32_bf16 v[86:89], v[206:209], v[190:193], v[86:89]
	v_mfma_f32_16x16x32_bf16 v[82:85], v[214:217], v[190:193], v[82:85]
	v_mfma_f32_16x16x32_bf16 v[70:73], v[206:209], v[198:201], v[70:73]
	v_mfma_f32_16x16x32_bf16 v[66:69], v[214:217], v[198:201], v[66:69]
	s_setprio 0
	s_mov_b32 m0, s30
	v_lshl_add_u64 v[222:223], s[24:25], 0, v[132:133]
	s_barrier
	ds_read_b128 v[170:173], v160 offset:16384
	ds_read_b128 v[174:177], v160 offset:17408
	ds_read_b128 v[178:181], v160 offset:18432
	ds_read_b128 v[182:185], v160 offset:19456
	ds_read_b128 v[186:189], v160 offset:20480
	ds_read_b128 v[190:193], v160 offset:21504
	ds_read_b128 v[194:197], v160 offset:22528
	ds_read_b128 v[198:201], v160 offset:23552
	global_load_lds_dwordx4 v[222:223], off
	v_lshl_add_u64 v[224:225], s[24:25], 0, v[136:137]
	s_mov_b32 m0, s31
	s_nop 0
	global_load_lds_dwordx4 v[224:225], off
	s_barrier
	s_waitcnt lgkmcnt(0)
	s_setprio 1
	s_waitcnt lgkmcnt(0)
	v_mfma_f32_16x16x32_bf16 v[62:65], v[150:153], v[170:173], v[62:65]
	v_mfma_f32_16x16x32_bf16 v[58:61], v[162:165], v[170:173], v[58:61]
	v_mfma_f32_16x16x32_bf16 v[46:49], v[150:153], v[178:181], v[46:49]
	v_mfma_f32_16x16x32_bf16 v[42:45], v[162:165], v[178:181], v[42:45]
	v_mfma_f32_16x16x32_bf16 v[30:33], v[150:153], v[186:189], v[30:33]
	v_mfma_f32_16x16x32_bf16 v[26:29], v[162:165], v[186:189], v[26:29]
	v_mfma_f32_16x16x32_bf16 v[14:17], v[150:153], v[194:197], v[14:17]
	v_mfma_f32_16x16x32_bf16 v[10:13], v[162:165], v[194:197], v[10:13]
	v_mfma_f32_16x16x32_bf16 v[62:65], v[154:157], v[174:177], v[62:65]
	v_mfma_f32_16x16x32_bf16 v[58:61], v[166:169], v[174:177], v[58:61]
	v_mfma_f32_16x16x32_bf16 v[46:49], v[154:157], v[182:185], v[46:49]
	v_mfma_f32_16x16x32_bf16 v[42:45], v[166:169], v[182:185], v[42:45]
	v_mfma_f32_16x16x32_bf16 v[30:33], v[154:157], v[190:193], v[30:33]
	v_mfma_f32_16x16x32_bf16 v[26:29], v[166:169], v[190:193], v[26:29]
	v_mfma_f32_16x16x32_bf16 v[14:17], v[154:157], v[198:201], v[14:17]
	v_mfma_f32_16x16x32_bf16 v[10:13], v[166:169], v[198:201], v[10:13]
	s_setprio 0
	s_barrier
; #define PG8_STAGE(bufoff, gbase, voff) do { _Pragma("unroll") for (int _i = 0; _i < 2; ++_i) \
;         __builtin_amdgcn_global_load_lds((const unsigned*)((const char*)(gbase) + (voff)[_i]), (PG8_LAS unsigned*)(lds + (bufoff) + ldsw + _i * 8192), 16, 0, 0); } while (0)
; #define PG8_LDA(dst, b, h) do { _Pragma("unroll") for (int m = 0; m < 4; ++m) _Pragma("unroll") for (int k = 0; k < 2; ++k) dst[m][k] = *(const PG8_LAS bf16x8*)(lds + PG8_SA(b, h) + aoff + m * 2048 + k * 1024); } while (0)
; #define PG8_LDB(dst, b, h) do { _Pragma("unroll") for (int n = 0; n < 2; ++n) _Pragma("unroll") for (int k = 0; k < 2; ++k) dst[n][k] = *(const PG8_LAS bf16x8*)(lds + PG8_SB(b, h) + boff + n * 2048 + k * 1024); } while (0)
; #define PG8_MMA(ai, bj, At, Bt) do { __builtin_amdgcn_s_setprio(1); _Pragma("unroll") for (int m = 0; m < 4; ++m) _Pragma("unroll") for (int n = 0; n < 2; ++n) _Pragma("unroll") for (int k = 0; k < 2; ++k) \
;         acc[ai][bj][m][n] = __builtin_amdgcn_mfma_f32_16x16x32_bf16(Bt[n][k], At[m][k], acc[ai][bj][m][n], 0, 0, 0); __builtin_amdgcn_s_setprio(0); } while (0)
; #define PG8_WAIT_V(n) asm volatile("s_waitcnt vmcnt(" #n ")" ::: "memory")
; #define PG8_WAIT_L(n) asm volatile("s_waitcnt lgkmcnt(" #n ")" ::: "memory")
; #define PG8_BAR __builtin_amdgcn_s_barrier()
; #define PG8_SCHED __builtin_amdgcn_sched_barrier(0)
; template <class Epi>
; __device__ __forceinline__ void gemm_phase(PG8_LAS unsigned char* lds, const Gemm g, const StaticOrder& S, const Epi& E) {
;     ...
;             PG8_STAGE(PG8_SB(0, 1), b2 + hstep, voffB);
;             PG8_WAIT_V(6); PG8_BAR; PG8_MMA(1, 1, At, B1); PG8_BAR;
;             PG8_LDB(B0, 1, 0); PG8_SCHED; PG8_LDA(At, 1, 0); PG8_STAGE(PG8_SA(0, 1), a2 + hstep, voffA);
;             PG8_WAIT_L(8); PG8_BAR; PG8_WAIT_L(0); PG8_MMA(0, 0, At, B0); PG8_BAR; PG8_SCHED;
;             PG8_LDB(B1, 1, 1); PG8_STAGE(PG8_SB(1, 0), b3, voffB);
;             PG8_BAR; PG8_WAIT_L(0); PG8_MMA(0, 1, At, B1); PG8_BAR;
	s_add_u32 s52, s22, 0x80000
	s_addc_u32 s53, s23, 0
	s_add_i32 s51, s44, s29
	v_lshl_add_u64 v[150:151], s[52:53], 0, v[134:135]
	s_mov_b32 m0, s51
	s_nop 0
	global_load_lds_dwordx4 v[150:151], off
	v_lshl_add_u64 v[150:151], s[52:53], 0, v[138:139]
	s_add_i32 m0, s51, 0x2000
	s_nop 0
	global_load_lds_dwordx4 v[150:151], off
	s_waitcnt vmcnt(10)
	s_barrier
	s_setprio 1
	v_mfma_f32_16x16x32_bf16 v[54:57], v[202:205], v[170:173], v[54:57]
	v_mfma_f32_16x16x32_bf16 v[50:53], v[210:213], v[170:173], v[50:53]
	v_mfma_f32_16x16x32_bf16 v[38:41], v[202:205], v[178:181], v[38:41]
	v_mfma_f32_16x16x32_bf16 v[34:37], v[210:213], v[178:181], v[34:37]
	v_mfma_f32_16x16x32_bf16 v[22:25], v[202:205], v[186:189], v[22:25]
	v_mfma_f32_16x16x32_bf16 v[18:21], v[210:213], v[186:189], v[18:21]
	v_mfma_f32_16x16x32_bf16 v[6:9], v[202:205], v[194:197], v[6:9]
	v_mfma_f32_16x16x32_bf16 v[2:5], v[210:213], v[194:197], v[2:5]
	v_mfma_f32_16x16x32_bf16 v[54:57], v[206:209], v[174:177], v[54:57]
	v_mfma_f32_16x16x32_bf16 v[50:53], v[214:217], v[174:177], v[50:53]
	v_mfma_f32_16x16x32_bf16 v[38:41], v[206:209], v[182:185], v[38:41]
	v_mfma_f32_16x16x32_bf16 v[34:37], v[214:217], v[182:185], v[34:37]
	v_mfma_f32_16x16x32_bf16 v[22:25], v[206:209], v[190:193], v[22:25]
	v_mfma_f32_16x16x32_bf16 v[18:21], v[214:217], v[190:193], v[18:21]
	v_mfma_f32_16x16x32_bf16 v[6:9], v[206:209], v[198:201], v[6:9]
	v_mfma_f32_16x16x32_bf16 v[2:5], v[214:217], v[198:201], v[2:5]
	s_setprio 0
	s_add_i32 s51, 0, 0x18000
	v_add_u32_e32 v140, s51, v131
	s_barrier
	ds_read_b128 v[150:153], v140
	ds_read_b128 v[154:157], v140 offset:1024
	ds_read_b128 v[162:165], v140 offset:2048
	ds_read_b128 v[166:169], v140 offset:3072
	s_add_u32 s24, s24, 0x80000
	s_addc_u32 s25, s25, 0
	s_mov_b32 m0, s33
	v_lshl_add_u64 v[202:203], s[24:25], 0, v[132:133]
	ds_read_b128 v[170:173], v160 offset:32768
	ds_read_b128 v[174:177], v160 offset:33792
	ds_read_b128 v[178:181], v160 offset:34816
	ds_read_b128 v[182:185], v160 offset:35840
	ds_read_b128 v[186:189], v160 offset:36864
	ds_read_b128 v[190:193], v160 offset:37888
	ds_read_b128 v[194:197], v160 offset:38912
	ds_read_b128 v[198:201], v160 offset:39936
	global_load_lds_dwordx4 v[202:203], off
	v_lshl_add_u64 v[202:203], s[24:25], 0, v[136:137]
	s_mov_b32 m0, s34
	s_nop 0
	global_load_lds_dwordx4 v[202:203], off
	s_waitcnt lgkmcnt(8)
	s_waitcnt vmcnt(10)
	s_barrier
	s_waitcnt lgkmcnt(0)
	s_setprio 1
	s_waitcnt lgkmcnt(0)
	v_mfma_f32_16x16x32_bf16 v[126:129], v[150:153], v[170:173], v[126:129]
	v_mfma_f32_16x16x32_bf16 v[122:125], v[162:165], v[170:173], v[122:125]
	v_mfma_f32_16x16x32_bf16 v[110:113], v[150:153], v[178:181], v[110:113]
	v_mfma_f32_16x16x32_bf16 v[106:109], v[162:165], v[178:181], v[106:109]
	v_mfma_f32_16x16x32_bf16 v[94:97], v[150:153], v[186:189], v[94:97]
	v_mfma_f32_16x16x32_bf16 v[90:93], v[162:165], v[186:189], v[90:93]
	v_mfma_f32_16x16x32_bf16 v[78:81], v[150:153], v[194:197], v[78:81]
	v_mfma_f32_16x16x32_bf16 v[74:77], v[162:165], v[194:197], v[74:77]
	v_mfma_f32_16x16x32_bf16 v[126:129], v[154:157], v[174:177], v[126:129]
	v_mfma_f32_16x16x32_bf16 v[122:125], v[166:169], v[174:177], v[122:125]
	v_mfma_f32_16x16x32_bf16 v[110:113], v[154:157], v[182:185], v[110:113]
	v_mfma_f32_16x16x32_bf16 v[106:109], v[166:169], v[182:185], v[106:109]
	v_mfma_f32_16x16x32_bf16 v[94:97], v[154:157], v[190:193], v[94:97]
	v_mfma_f32_16x16x32_bf16 v[90:93], v[166:169], v[190:193], v[90:93]
	v_mfma_f32_16x16x32_bf16 v[78:81], v[154:157], v[198:201], v[78:81]
	v_mfma_f32_16x16x32_bf16 v[74:77], v[166:169], v[198:201], v[74:77]
	s_setprio 0
	s_barrier
	s_add_i32 s24, 0, 0x1c000
	s_add_i32 s25, s51, s29
	v_add_u32_e32 v140, s24, v131
	v_lshl_add_u64 v[218:219], v[218:219], 0, s[10:11]
	s_mov_b32 m0, s25
	ds_read_b128 v[202:205], v140
	ds_read_b128 v[206:209], v140 offset:1024
	ds_read_b128 v[210:213], v140 offset:2048
	ds_read_b128 v[214:217], v140 offset:3072
	global_load_lds_dwordx4 v[218:219], off
	v_lshl_add_u64 v[218:219], v[220:221], 0, s[10:11]
	s_add_i32 m0, s25, 0x2000
	s_nop 0
	global_load_lds_dwordx4 v[218:219], off
	s_waitcnt vmcnt(10)
	s_barrier
; #define PG8_STAGE(bufoff, gbase, voff) do { _Pragma("unroll") for (int _i = 0; _i < 2; ++_i) \
;         __builtin_amdgcn_global_load_lds((const unsigned*)((const char*)(gbase) + (voff)[_i]), (PG8_LAS unsigned*)(lds + (bufoff) + ldsw + _i * 8192), 16, 0, 0); } while (0)
; #define PG8_LDA(dst, b, h) do { _Pragma("unroll") for (int m = 0; m < 4; ++m) _Pragma("unroll") for (int k = 0; k < 2; ++k) dst[m][k] = *(const PG8_LAS bf16x8*)(lds + PG8_SA(b, h) + aoff + m * 2048 + k * 1024); } while (0)
; #define PG8_MMA(ai, bj, At, Bt) do { __builtin_amdgcn_s_setprio(1); _Pragma("unroll") for (int m = 0; m < 4; ++m) _Pragma("unroll") for (int n = 0; n < 2; ++n) _Pragma("unroll") for (int k = 0; k < 2; ++k) \
;         acc[ai][bj][m][n] = __builtin_amdgcn_mfma_f32_16x16x32_bf16(Bt[n][k], At[m][k], acc[ai][bj][m][n], 0, 0, 0); __builtin_amdgcn_s_setprio(0); } while (0)
; #define PG8_WAIT_V(n) asm volatile("s_waitcnt vmcnt(" #n ")" ::: "memory")
; #define PG8_WAIT_L(n) asm volatile("s_waitcnt lgkmcnt(" #n ")" ::: "memory")
; #define PG8_BAR __builtin_amdgcn_s_barrier()
; #define PG8_SCHED __builtin_amdgcn_sched_barrier(0)
; template <class Epi>
; __device__ __forceinline__ void gemm_phase(PG8_LAS unsigned char* lds, const Gemm g, const StaticOrder& S, const Epi& E) {
;     ...
;             PG8_LDA(At, 1, 1); PG8_STAGE(PG8_SA(1, 0), a3, voffA);
;             PG8_BAR; PG8_WAIT_L(0); PG8_MMA(1, 0, At, B0); PG8_BAR; PG8_SCHED;
;             PG8_STAGE(PG8_SB(1, 1), b3 + hstep, voffB);
;             PG8_WAIT_V(6); PG8_BAR; PG8_MMA(1, 1, At, B1); PG8_BAR;
;         }
;         E(acc, cur, wr, wc, fr, fq);
	s_waitcnt lgkmcnt(0)
	s_setprio 1
	s_waitcnt lgkmcnt(0)
	v_mfma_f32_16x16x32_bf16 v[118:121], v[202:205], v[170:173], v[118:121]
	v_mfma_f32_16x16x32_bf16 v[114:117], v[210:213], v[170:173], v[114:117]
	v_mfma_f32_16x16x32_bf16 v[102:105], v[202:205], v[178:181], v[102:105]
	v_mfma_f32_16x16x32_bf16 v[98:101], v[210:213], v[178:181], v[98:101]
	v_mfma_f32_16x16x32_bf16 v[86:89], v[202:205], v[186:189], v[86:89]
	v_mfma_f32_16x16x32_bf16 v[82:85], v[210:213], v[186:189], v[82:85]
	v_mfma_f32_16x16x32_bf16 v[70:73], v[202:205], v[194:197], v[70:73]
	v_mfma_f32_16x16x32_bf16 v[66:69], v[210:213], v[194:197], v[66:69]
	v_mfma_f32_16x16x32_bf16 v[118:121], v[206:209], v[174:177], v[118:121]
	v_mfma_f32_16x16x32_bf16 v[114:117], v[214:217], v[174:177], v[114:117]
	v_mfma_f32_16x16x32_bf16 v[102:105], v[206:209], v[182:185], v[102:105]
	v_mfma_f32_16x16x32_bf16 v[98:101], v[214:217], v[182:185], v[98:101]
	v_mfma_f32_16x16x32_bf16 v[86:89], v[206:209], v[190:193], v[86:89]
	v_mfma_f32_16x16x32_bf16 v[82:85], v[214:217], v[190:193], v[82:85]
	v_mfma_f32_16x16x32_bf16 v[70:73], v[206:209], v[198:201], v[70:73]
	v_mfma_f32_16x16x32_bf16 v[66:69], v[214:217], v[198:201], v[66:69]
	s_setprio 0
	s_mov_b32 m0, s38
	v_lshl_add_u64 v[218:219], v[222:223], 0, s[10:11]
	s_barrier
	ds_read_b128 v[170:173], v160 offset:49152
	ds_read_b128 v[174:177], v160 offset:50176
	ds_read_b128 v[178:181], v160 offset:51200
	ds_read_b128 v[182:185], v160 offset:52224
	ds_read_b128 v[186:189], v160 offset:53248
	ds_read_b128 v[190:193], v160 offset:54272
	ds_read_b128 v[194:197], v160 offset:55296
	ds_read_b128 v[198:201], v160 offset:56320
	global_load_lds_dwordx4 v[218:219], off
	v_lshl_add_u64 v[218:219], v[224:225], 0, s[10:11]
	s_mov_b32 m0, s39
	s_nop 0
	global_load_lds_dwordx4 v[218:219], off
	s_barrier
	s_waitcnt lgkmcnt(0)
	s_setprio 1
	s_waitcnt lgkmcnt(0)
	v_mfma_f32_16x16x32_bf16 v[62:65], v[150:153], v[170:173], v[62:65]
	v_mfma_f32_16x16x32_bf16 v[58:61], v[162:165], v[170:173], v[58:61]
	v_mfma_f32_16x16x32_bf16 v[46:49], v[150:153], v[178:181], v[46:49]
	v_mfma_f32_16x16x32_bf16 v[42:45], v[162:165], v[178:181], v[42:45]
	v_mfma_f32_16x16x32_bf16 v[30:33], v[150:153], v[186:189], v[30:33]
	v_mfma_f32_16x16x32_bf16 v[26:29], v[162:165], v[186:189], v[26:29]
	v_mfma_f32_16x16x32_bf16 v[14:17], v[150:153], v[194:197], v[14:17]
	v_mfma_f32_16x16x32_bf16 v[10:13], v[162:165], v[194:197], v[10:13]
	v_mfma_f32_16x16x32_bf16 v[62:65], v[154:157], v[174:177], v[62:65]
	v_mfma_f32_16x16x32_bf16 v[58:61], v[166:169], v[174:177], v[58:61]
	v_mfma_f32_16x16x32_bf16 v[46:49], v[154:157], v[182:185], v[46:49]
	v_mfma_f32_16x16x32_bf16 v[42:45], v[166:169], v[182:185], v[42:45]
	v_mfma_f32_16x16x32_bf16 v[30:33], v[154:157], v[190:193], v[30:33]
	v_mfma_f32_16x16x32_bf16 v[26:29], v[166:169], v[190:193], v[26:29]
	v_mfma_f32_16x16x32_bf16 v[14:17], v[154:157], v[198:201], v[14:17]
	v_mfma_f32_16x16x32_bf16 v[10:13], v[166:169], v[198:201], v[10:13]
	s_setprio 0
	s_barrier
	s_add_u32 s22, s22, 0x80080
	s_addc_u32 s23, s23, 0
	s_add_i32 s24, s24, s29
	v_lshl_add_u64 v[150:151], s[22:23], 0, v[134:135]
	s_mov_b32 m0, s24
	s_nop 0
	global_load_lds_dwordx4 v[150:151], off
	v_lshl_add_u64 v[150:151], s[22:23], 0, v[138:139]
	s_add_i32 m0, s24, 0x2000
	s_nop 0
	global_load_lds_dwordx4 v[150:151], off
	s_waitcnt vmcnt(10)
	s_barrier
	s_setprio 1
	v_mfma_f32_16x16x32_bf16 v[54:57], v[202:205], v[170:173], v[54:57]
	v_mfma_f32_16x16x32_bf16 v[50:53], v[210:213], v[170:173], v[50:53]
	v_mfma_f32_16x16x32_bf16 v[38:41], v[202:205], v[178:181], v[38:41]
	v_mfma_f32_16x16x32_bf16 v[34:37], v[210:213], v[178:181], v[34:37]
	v_mfma_f32_16x16x32_bf16 v[22:25], v[202:205], v[186:189], v[22:25]
	v_mfma_f32_16x16x32_bf16 v[18:21], v[210:213], v[186:189], v[18:21]
	v_mfma_f32_16x16x32_bf16 v[6:9], v[202:205], v[194:197], v[6:9]
	v_mfma_f32_16x16x32_bf16 v[2:5], v[210:213], v[194:197], v[2:5]
	v_mfma_f32_16x16x32_bf16 v[54:57], v[206:209], v[174:177], v[54:57]
	v_mfma_f32_16x16x32_bf16 v[50:53], v[214:217], v[174:177], v[50:53]
	v_mfma_f32_16x16x32_bf16 v[38:41], v[206:209], v[182:185], v[38:41]
	v_mfma_f32_16x16x32_bf16 v[34:37], v[214:217], v[182:185], v[34:37]
	v_mfma_f32_16x16x32_bf16 v[22:25], v[206:209], v[190:193], v[22:25]
	v_mfma_f32_16x16x32_bf16 v[18:21], v[214:217], v[190:193], v[18:21]
	v_mfma_f32_16x16x32_bf16 v[6:9], v[206:209], v[198:201], v[6:9]
	v_mfma_f32_16x16x32_bf16 v[2:5], v[214:217], v[198:201], v[2:5]
	s_setprio 0
	s_add_i32 s50, s50, 2
	s_add_u32 s20, s20, 0x100
	s_addc_u32 s21, s21, 0
	s_add_u32 s48, s48, 0x100
	s_addc_u32 s49, s49, 0
	s_cmp_gt_u32 s50, 29
	s_barrier
	s_cbranch_scc0 .LBB0_722
	v_lshl_add_u32 v152, s2, 8, v1
	s_lshl_b32 s13, s4, 8
	v_or_b32_e32 v150, s13, v158
	v_mad_i64_i32 v[154:155], s[2:3], v152, s45, 0
	v_cmp_lt_i32_e64 s[2:3], s46, v150
	s_and_saveexec_b64 s[20:21], s[2:3]
	s_xor_b64 s[20:21], exec, s[20:21]
	s_cbranch_execz .LBB0_726
	s_cmpk_gt_u32 s13, 0x317f
	s_cbranch_scc1 .LBB0_726
	v_lshl_add_u64 v[156:157], s[8:9], 0, v[154:155]
	v_mov_b32_e32 v151, v141
	v_lshl_add_u64 v[156:157], v[150:151], 1, v[156:157]
	v_add_co_u32_e32 v156, vcc, 0xffffa000, v156
	v_cvt_pk_bf16_f32 v162, v126, v127
	v_cvt_pk_bf16_f32 v163, v128, v129
	v_cvt_pk_bf16_f32 v164, v122, v123
	v_cvt_pk_bf16_f32 v165, v124, v125
	s_nop 1
	v_addc_co_u32_e32 v157, vcc, -1, v157, vcc
	global_store_dwordx4 v[156:157], v[162:165], off
